# gemm_in K-loop: first iteration peeled with relaxed vmcnt waits so the first two super-phases of a tile overlap the previous tile's store drain
# baseline (speedup 1.0000x reference)
; #define PG8_STAGE(bufoff, gbase, voff) do { _Pragma("unroll") for (int _i = 0; _i < 2; ++_i) \
;         __builtin_amdgcn_global_load_lds((const unsigned*)((const char*)(gbase) + (voff)[_i]), (PG8_LAS unsigned*)(lds + (bufoff) + ldsw + _i * 8192), 16, 0, 0); } while (0)
; #define PG8_LDA(dst, b, h) do { _Pragma("unroll") for (int m = 0; m < 4; ++m) _Pragma("unroll") for (int k = 0; k < 2; ++k) dst[m][k] = *(const PG8_LAS bf16x8*)(lds + PG8_SA(b, h) + aoff + m * 2048 + k * 1024); } while (0)
; #define PG8_LDB(dst, b, h) do { _Pragma("unroll") for (int n = 0; n < 2; ++n) _Pragma("unroll") for (int k = 0; k < 2; ++k) dst[n][k] = *(const PG8_LAS bf16x8*)(lds + PG8_SB(b, h) + boff + n * 2048 + k * 1024); } while (0)
; #define PG8_WAIT_V(n) asm volatile("s_waitcnt vmcnt(" #n ")" ::: "memory")
; template <class Epi, class Sched, bool ALIGN_EPI = false, bool SP2 = false>
; __device__ __forceinline__ void gemm_phase(PG8_LAS unsigned char* lds, const Gemm g, const Sched& S, const Epi& E) {
;     ...
;         const bool has_next = S.next(ui + 1, nxt);
;         const char* nA = has_next ? (const char*)g.A + (size_t)nxt.pm * tstepA + (nxt.pn >= g.asplit ? (size_t)g.aoff2 * 2 : 0) : cA; const char* nB = has_next ? (const char*)g.Bt + (size_t)nxt.pn * tstepB : cB;
;         for (int t = 0; t < nt; t += 2) {
;             const bool last = (t == nt - 2);
;             if constexpr (Epi::MIDHOOK) { if (t == (nt >> 1)) E.mid(acc, cur, wr, wc); }
;             const char* a1 = cA + (size_t)(t + 1) * kstep;
;             const char* a2 = last ? nA : cA + (size_t)(t + 2) * kstep; const char* b2 = last ? nB : cB + (size_t)(t + 2) * kstep;
;             const char* a3 = a2 + kstep; const char* b3 = b2 + kstep;
;             if (last && has_next) S.a_ready(nxt);
;             if constexpr (SP2) {
;             PG8_LDB(B0, 0, 0); PG8_LDB(B1, 0, 1); PG8_SCHED; PG8_LDA(At, 0, 0); PG8_STAGE(PG8_SA(1, 1), a1 + hstepA, voffA);
;             PG8_WAIT_V(8); PG8_WAIT_L(0); PG8_BAR; PG8_MMA(0, 0, At, B0); PG8_MMA(0, 1, At, B1); PG8_BAR; PG8_SCHED;
;     ...
;         for (int a = 0; a < 2; ++a)
; #pragma unroll
;             for (int b = 0; b < 2; ++b)
; #pragma unroll
;                 for (int m = 0; m < 4; ++m)
; #pragma unroll
;                     for (int n = 0; n < 2; ++n) acc[a][b][m][n] = (f32x4){0.f, 0.f, 0.f, 0.f};
;         cur = nxt; cA = nA; cB = nB; ++ui;
.LBB0_551:
	s_ashr_i32 s63, s62, 31
	s_lshl_b64 s[38:39], s[62:63], 19
	s_add_u32 s64, s92, s38
	s_addc_u32 s65, s93, s39
	s_and_b64 s[38:39], s[40:41], exec
	s_cselect_b32 s3, s65, s35
	s_cselect_b32 s30, s64, s34
	s_ashr_i32 s61, s60, 31
	s_lshl_b64 s[38:39], s[60:61], 19
	s_add_u32 s66, s5, s38
	s_addc_u32 s67, s72, s39
	s_and_b64 s[38:39], s[40:41], exec
	s_cselect_b32 s37, s67, s7
	s_cselect_b32 s42, s66, s6
	s_add_u32 s43, s6, 0x100
	s_addc_u32 s44, s7, 0
	s_add_u32 s6, s34, 0x40080
	v_mov_b32_e32 v2, 0
	s_addc_u32 s7, s35, 0
	s_mov_b32 s45, -2
	v_mov_b32_e32 v3, v2
	v_mov_b32_e32 v4, v2
	v_mov_b32_e32 v5, v2
	v_mov_b32_e32 v6, v2
	v_mov_b32_e32 v7, v2
	v_mov_b32_e32 v8, v2
	v_mov_b32_e32 v9, v2
	v_mov_b32_e32 v18, v2
	v_mov_b32_e32 v19, v2
	v_mov_b32_e32 v20, v2
	v_mov_b32_e32 v21, v2
	v_mov_b32_e32 v22, v2
	v_mov_b32_e32 v23, v2
	v_mov_b32_e32 v24, v2
	v_mov_b32_e32 v25, v2
	v_mov_b32_e32 v34, v2
	v_mov_b32_e32 v35, v2
	v_mov_b32_e32 v36, v2
	v_mov_b32_e32 v37, v2
	v_mov_b32_e32 v38, v2
	v_mov_b32_e32 v39, v2
	v_mov_b32_e32 v40, v2
	v_mov_b32_e32 v41, v2
	v_mov_b32_e32 v50, v2
	v_mov_b32_e32 v51, v2
	v_mov_b32_e32 v52, v2
	v_mov_b32_e32 v53, v2
	v_mov_b32_e32 v54, v2
	v_mov_b32_e32 v55, v2
	v_mov_b32_e32 v56, v2
	v_mov_b32_e32 v57, v2
	v_mov_b32_e32 v10, v2
	v_mov_b32_e32 v11, v2
	v_mov_b32_e32 v12, v2
	v_mov_b32_e32 v13, v2
	v_mov_b32_e32 v14, v2
	v_mov_b32_e32 v15, v2
	v_mov_b32_e32 v16, v2
	v_mov_b32_e32 v17, v2
	v_mov_b32_e32 v26, v2
	v_mov_b32_e32 v27, v2
	v_mov_b32_e32 v28, v2
	v_mov_b32_e32 v29, v2
	v_mov_b32_e32 v30, v2
	v_mov_b32_e32 v31, v2
	v_mov_b32_e32 v32, v2
	v_mov_b32_e32 v33, v2
	v_mov_b32_e32 v42, v2
	v_mov_b32_e32 v43, v2
	v_mov_b32_e32 v44, v2
	v_mov_b32_e32 v45, v2
	v_mov_b32_e32 v46, v2
	v_mov_b32_e32 v47, v2
	v_mov_b32_e32 v48, v2
	v_mov_b32_e32 v49, v2
	v_mov_b32_e32 v58, v2
	v_mov_b32_e32 v59, v2
	v_mov_b32_e32 v60, v2
	v_mov_b32_e32 v61, v2
	v_mov_b32_e32 v62, v2
	v_mov_b32_e32 v63, v2
	v_mov_b32_e32 v64, v2
	v_mov_b32_e32 v65, v2
	v_mov_b32_e32 v66, v2
	v_mov_b32_e32 v67, v2
	v_mov_b32_e32 v68, v2
	v_mov_b32_e32 v69, v2
	v_mov_b32_e32 v70, v2
	v_mov_b32_e32 v71, v2
	v_mov_b32_e32 v72, v2
	v_mov_b32_e32 v73, v2
	v_mov_b32_e32 v82, v2
	v_mov_b32_e32 v83, v2
	v_mov_b32_e32 v84, v2
	v_mov_b32_e32 v85, v2
	v_mov_b32_e32 v86, v2
	v_mov_b32_e32 v87, v2
	v_mov_b32_e32 v88, v2
	v_mov_b32_e32 v89, v2
	v_mov_b32_e32 v114, v2
	v_mov_b32_e32 v115, v2
	v_mov_b32_e32 v116, v2
	v_mov_b32_e32 v117, v2
	v_mov_b32_e32 v118, v2
	v_mov_b32_e32 v119, v2
	v_mov_b32_e32 v120, v2
	v_mov_b32_e32 v121, v2
	v_mov_b32_e32 v130, v2
	v_mov_b32_e32 v131, v2
	v_mov_b32_e32 v132, v2
	v_mov_b32_e32 v133, v2
	v_mov_b32_e32 v134, v2
	v_mov_b32_e32 v135, v2
	v_mov_b32_e32 v136, v2
	v_mov_b32_e32 v137, v2
	v_mov_b32_e32 v74, v2
	v_mov_b32_e32 v75, v2
	v_mov_b32_e32 v76, v2
	v_mov_b32_e32 v77, v2
	v_mov_b32_e32 v78, v2
	v_mov_b32_e32 v79, v2
	v_mov_b32_e32 v80, v2
	v_mov_b32_e32 v81, v2
	s_waitcnt vmcnt(0)
	v_mov_b32_e32 v98, v2
	v_mov_b32_e32 v99, v2
	v_mov_b32_e32 v100, v2
	v_mov_b32_e32 v101, v2
	v_mov_b32_e32 v102, v2
	v_mov_b32_e32 v103, v2
	v_mov_b32_e32 v104, v2
	v_mov_b32_e32 v105, v2
	v_mov_b32_e32 v122, v2
	v_mov_b32_e32 v123, v2
	v_mov_b32_e32 v124, v2
	v_mov_b32_e32 v125, v2
	v_mov_b32_e32 v126, v2
	v_mov_b32_e32 v127, v2
	v_mov_b32_e32 v128, v2
	v_mov_b32_e32 v129, v2
	v_mov_b32_e32 v138, v2
	v_mov_b32_e32 v139, v2
	v_mov_b32_e32 v140, v2
	v_mov_b32_e32 v141, v2
	v_mov_b32_e32 v142, v2
	v_mov_b32_e32 v143, v2
	v_mov_b32_e32 v144, v2
	v_mov_b32_e32 v145, v2
	s_add_u32 s34, s6, 0xfffc0080
	s_addc_u32 s35, s7, -1
	s_add_i32 s47, 0, 0x10000
	s_cmp_eq_u32 s45, 12
	s_cselect_b32 s39, s3, s35
	s_cselect_b32 s38, s30, s34
	v_add_u32_e32 v0, s47, v161
	s_cselect_b32 s35, s37, s44
	s_cselect_b32 s34, s42, s43
	s_add_i32 s57, 0, 0x14000
	ds_read_b128 v[90:93], v0
	ds_read_b128 v[94:97], v0 offset:1024
	ds_read_b128 v[106:109], v0 offset:2048
	ds_read_b128 v[110:113], v0 offset:3072
	v_add_u32_e32 v0, s57, v161
	ds_read_b128 v[164:167], v0
	ds_read_b128 v[168:171], v0 offset:1024
	ds_read_b128 v[172:175], v0 offset:2048
	ds_read_b128 v[176:179], v0 offset:3072
	v_lshl_add_u64 v[158:159], s[6:7], 0, v[156:157]
	s_add_i32 m0, s86, 0xc000
	ds_read_b128 v[180:183], v163
	ds_read_b128 v[184:187], v163 offset:1024
	ds_read_b128 v[188:191], v163 offset:2048
	ds_read_b128 v[208:211], v163 offset:3072
	ds_read_b128 v[212:215], v163 offset:4096
	ds_read_b128 v[216:219], v163 offset:5120
	ds_read_b128 v[234:237], v163 offset:6144
	ds_read_b128 v[238:241], v163 offset:7168
	global_load_lds_dwordx4 v[158:159], off
	v_lshl_add_u64 v[158:159], s[6:7], 0, v[154:155]
	s_add_i32 m0, s86, 0xe000
	s_nop 0
	global_load_lds_dwordx4 v[158:159], off
	s_waitcnt vmcnt(63)
	s_waitcnt lgkmcnt(0)
	s_barrier
; #define PG8_STAGE(bufoff, gbase, voff) do { _Pragma("unroll") for (int _i = 0; _i < 2; ++_i) \
;         __builtin_amdgcn_global_load_lds((const unsigned*)((const char*)(gbase) + (voff)[_i]), (PG8_LAS unsigned*)(lds + (bufoff) + ldsw + _i * 8192), 16, 0, 0); } while (0)
; #define PG8_LDA(dst, b, h) do { _Pragma("unroll") for (int m = 0; m < 4; ++m) _Pragma("unroll") for (int k = 0; k < 2; ++k) dst[m][k] = *(const PG8_LAS bf16x8*)(lds + PG8_SA(b, h) + aoff + m * 2048 + k * 1024); } while (0)
; #define PG8_MMA(ai, bj, At, Bt) do { __builtin_amdgcn_s_setprio(1); _Pragma("unroll") for (int m = 0; m < 4; ++m) _Pragma("unroll") for (int n = 0; n < 2; ++n) _Pragma("unroll") for (int k = 0; k < 2; ++k) \
;         acc[ai][bj][m][n] = __builtin_amdgcn_mfma_f32_16x16x32_bf16(Bt[n][k], At[m][k], acc[ai][bj][m][n], 0, 0, 0); __builtin_amdgcn_s_setprio(0); } while (0)
; #define PG8_WAIT_V(n) asm volatile("s_waitcnt vmcnt(" #n ")" ::: "memory")
; #define PG8_WAIT_L(n) asm volatile("s_waitcnt lgkmcnt(" #n ")" ::: "memory")
; #define PG8_BAR __builtin_amdgcn_s_barrier()
; #define PG8_SCHED __builtin_amdgcn_sched_barrier(0)
; template <class Epi, class Sched, bool ALIGN_EPI = false, bool SP2 = false>
; __device__ __forceinline__ void gemm_phase(PG8_LAS unsigned char* lds, const Gemm g, const Sched& S, const Epi& E) {
;     ...
;             PG8_WAIT_V(8); PG8_WAIT_L(0); PG8_BAR; PG8_MMA(0, 0, At, B0); PG8_MMA(0, 1, At, B1); PG8_BAR; PG8_SCHED;
;             PG8_LDA(At, 0, 1); PG8_STAGE(PG8_SB(0, 0), b2, voffB); PG8_STAGE(PG8_SB(0, 1), b2 + hstepB, voffB); PG8_STAGE(PG8_SA(0, 0), a2, voffA);
;             PG8_WAIT_V(8); PG8_WAIT_L(0); PG8_BAR; PG8_MMA(1, 0, At, B0); PG8_MMA(1, 1, At, B1); PG8_BAR; PG8_SCHED;
	s_setprio 1
	s_waitcnt lgkmcnt(0)
	v_mfma_f32_16x16x32_bf16 v[142:145], v[90:93], v[180:183], v[142:145]
	v_mfma_f32_16x16x32_bf16 v[138:141], v[106:109], v[180:183], v[138:141]
	v_mfma_f32_16x16x32_bf16 v[126:129], v[90:93], v[188:191], v[126:129]
	v_mfma_f32_16x16x32_bf16 v[122:125], v[106:109], v[188:191], v[122:125]
	v_mfma_f32_16x16x32_bf16 v[102:105], v[90:93], v[212:215], v[102:105]
	v_mfma_f32_16x16x32_bf16 v[98:101], v[106:109], v[212:215], v[98:101]
	v_mfma_f32_16x16x32_bf16 v[78:81], v[90:93], v[234:237], v[78:81]
	v_mfma_f32_16x16x32_bf16 v[74:77], v[106:109], v[234:237], v[74:77]
	v_mfma_f32_16x16x32_bf16 v[142:145], v[94:97], v[184:187], v[142:145]
	v_mfma_f32_16x16x32_bf16 v[138:141], v[110:113], v[184:187], v[138:141]
	v_mfma_f32_16x16x32_bf16 v[126:129], v[94:97], v[208:211], v[126:129]
	v_mfma_f32_16x16x32_bf16 v[122:125], v[110:113], v[208:211], v[122:125]
	v_mfma_f32_16x16x32_bf16 v[102:105], v[94:97], v[216:219], v[102:105]
	v_mfma_f32_16x16x32_bf16 v[98:101], v[110:113], v[216:219], v[98:101]
	v_mfma_f32_16x16x32_bf16 v[78:81], v[94:97], v[238:241], v[78:81]
	v_mfma_f32_16x16x32_bf16 v[74:77], v[110:113], v[238:241], v[74:77]
	s_setprio 0
	s_setprio 1
	v_mfma_f32_16x16x32_bf16 v[134:137], v[164:167], v[180:183], v[134:137]
	v_mfma_f32_16x16x32_bf16 v[130:133], v[172:175], v[180:183], v[130:133]
	v_mfma_f32_16x16x32_bf16 v[118:121], v[164:167], v[188:191], v[118:121]
	v_mfma_f32_16x16x32_bf16 v[114:117], v[172:175], v[188:191], v[114:117]
	v_mfma_f32_16x16x32_bf16 v[86:89], v[164:167], v[212:215], v[86:89]
	v_mfma_f32_16x16x32_bf16 v[82:85], v[172:175], v[212:215], v[82:85]
	v_mfma_f32_16x16x32_bf16 v[70:73], v[164:167], v[234:237], v[70:73]
	v_mfma_f32_16x16x32_bf16 v[66:69], v[172:175], v[234:237], v[66:69]
	v_mfma_f32_16x16x32_bf16 v[134:137], v[168:171], v[184:187], v[134:137]
	v_mfma_f32_16x16x32_bf16 v[130:133], v[176:179], v[184:187], v[130:133]
	v_mfma_f32_16x16x32_bf16 v[118:121], v[168:171], v[208:211], v[118:121]
	v_mfma_f32_16x16x32_bf16 v[114:117], v[176:179], v[208:211], v[114:117]
	v_mfma_f32_16x16x32_bf16 v[86:89], v[168:171], v[216:219], v[86:89]
	v_mfma_f32_16x16x32_bf16 v[82:85], v[176:179], v[216:219], v[82:85]
	v_mfma_f32_16x16x32_bf16 v[70:73], v[168:171], v[238:241], v[70:73]
	v_mfma_f32_16x16x32_bf16 v[66:69], v[176:179], v[238:241], v[66:69]
	s_setprio 0
	s_barrier
	s_add_i32 s47, s47, s73
	v_lshl_add_u64 v[158:159], s[34:35], 0, v[148:149]
	s_mov_b32 m0, s47
	ds_read_b128 v[180:183], v163 offset:16384
	ds_read_b128 v[184:187], v163 offset:17408
	ds_read_b128 v[188:191], v163 offset:18432
	ds_read_b128 v[208:211], v163 offset:19456
	ds_read_b128 v[212:215], v163 offset:20480
	ds_read_b128 v[216:219], v163 offset:21504
	ds_read_b128 v[234:237], v163 offset:22528
	ds_read_b128 v[238:241], v163 offset:23552
	global_load_lds_dwordx4 v[158:159], off
	s_add_i32 m0, s47, 0x2000
	s_add_u32 s68, s34, 0x40000
	v_lshl_add_u64 v[192:193], s[34:35], 0, v[152:153]
	s_addc_u32 s69, s35, 0
	s_add_i32 s47, s57, s73
	global_load_lds_dwordx4 v[192:193], off
	v_lshl_add_u64 v[194:195], s[68:69], 0, v[148:149]
	s_mov_b32 m0, s47
	v_lshl_add_u64 v[196:197], s[38:39], 0, v[150:151]
	global_load_lds_dwordx4 v[194:195], off
	v_lshl_add_u64 v[194:195], s[68:69], 0, v[152:153]
	s_add_i32 m0, s47, 0x2000
	s_nop 0
	global_load_lds_dwordx4 v[194:195], off
	v_lshl_add_u64 v[194:195], s[38:39], 0, v[146:147]
	s_mov_b32 m0, s86
	s_nop 0
	global_load_lds_dwordx4 v[194:195], off
	s_mov_b32 m0, s87
	s_nop 0
	global_load_lds_dwordx4 v[196:197], off
	s_cmp_lg_u32 s48, 1
	s_cbranch_scc1 .Lpeel_gin_w2
	s_waitcnt vmcnt(8)
.Lpeel_gin_w2:
	s_waitcnt lgkmcnt(0)
	s_barrier
	s_setprio 1
	s_waitcnt lgkmcnt(0)
	v_mfma_f32_16x16x32_bf16 v[62:65], v[90:93], v[180:183], v[62:65]
	v_mfma_f32_16x16x32_bf16 v[58:61], v[106:109], v[180:183], v[58:61]
	v_mfma_f32_16x16x32_bf16 v[46:49], v[90:93], v[188:191], v[46:49]
	v_mfma_f32_16x16x32_bf16 v[42:45], v[106:109], v[188:191], v[42:45]
	v_mfma_f32_16x16x32_bf16 v[30:33], v[90:93], v[212:215], v[30:33]
	v_mfma_f32_16x16x32_bf16 v[26:29], v[106:109], v[212:215], v[26:29]
	v_mfma_f32_16x16x32_bf16 v[14:17], v[90:93], v[234:237], v[14:17]
	v_mfma_f32_16x16x32_bf16 v[10:13], v[106:109], v[234:237], v[10:13]
	v_mfma_f32_16x16x32_bf16 v[62:65], v[94:97], v[184:187], v[62:65]
	v_mfma_f32_16x16x32_bf16 v[58:61], v[110:113], v[184:187], v[58:61]
	v_mfma_f32_16x16x32_bf16 v[46:49], v[94:97], v[208:211], v[46:49]
	v_mfma_f32_16x16x32_bf16 v[42:45], v[110:113], v[208:211], v[42:45]
	v_mfma_f32_16x16x32_bf16 v[30:33], v[94:97], v[216:219], v[30:33]
	v_mfma_f32_16x16x32_bf16 v[26:29], v[110:113], v[216:219], v[26:29]
	v_mfma_f32_16x16x32_bf16 v[14:17], v[94:97], v[238:241], v[14:17]
	v_mfma_f32_16x16x32_bf16 v[10:13], v[110:113], v[238:241], v[10:13]
	s_setprio 0
	s_setprio 1
	v_mfma_f32_16x16x32_bf16 v[54:57], v[164:167], v[180:183], v[54:57]
	v_mfma_f32_16x16x32_bf16 v[50:53], v[172:175], v[180:183], v[50:53]
	v_mfma_f32_16x16x32_bf16 v[38:41], v[164:167], v[188:191], v[38:41]
	v_mfma_f32_16x16x32_bf16 v[34:37], v[172:175], v[188:191], v[34:37]
	v_mfma_f32_16x16x32_bf16 v[22:25], v[164:167], v[212:215], v[22:25]
	v_mfma_f32_16x16x32_bf16 v[18:21], v[172:175], v[212:215], v[18:21]
	v_mfma_f32_16x16x32_bf16 v[6:9], v[164:167], v[234:237], v[6:9]
	v_mfma_f32_16x16x32_bf16 v[2:5], v[172:175], v[234:237], v[2:5]
	v_mfma_f32_16x16x32_bf16 v[54:57], v[168:171], v[184:187], v[54:57]
	v_mfma_f32_16x16x32_bf16 v[50:53], v[176:179], v[184:187], v[50:53]
	v_mfma_f32_16x16x32_bf16 v[38:41], v[168:171], v[208:211], v[38:41]
	v_mfma_f32_16x16x32_bf16 v[34:37], v[176:179], v[208:211], v[34:37]
	v_mfma_f32_16x16x32_bf16 v[22:25], v[168:171], v[216:219], v[22:25]
	v_mfma_f32_16x16x32_bf16 v[18:21], v[176:179], v[216:219], v[18:21]
	v_mfma_f32_16x16x32_bf16 v[6:9], v[168:171], v[238:241], v[6:9]
	v_mfma_f32_16x16x32_bf16 v[2:5], v[176:179], v[238:241], v[2:5]
	s_setprio 0
	s_barrier
; #define PG8_STAGE(bufoff, gbase, voff) do { _Pragma("unroll") for (int _i = 0; _i < 2; ++_i) \
;         __builtin_amdgcn_global_load_lds((const unsigned*)((const char*)(gbase) + (voff)[_i]), (PG8_LAS unsigned*)(lds + (bufoff) + ldsw + _i * 8192), 16, 0, 0); } while (0)
; #define PG8_LDA(dst, b, h) do { _Pragma("unroll") for (int m = 0; m < 4; ++m) _Pragma("unroll") for (int k = 0; k < 2; ++k) dst[m][k] = *(const PG8_LAS bf16x8*)(lds + PG8_SA(b, h) + aoff + m * 2048 + k * 1024); } while (0)
; #define PG8_LDB(dst, b, h) do { _Pragma("unroll") for (int n = 0; n < 2; ++n) _Pragma("unroll") for (int k = 0; k < 2; ++k) dst[n][k] = *(const PG8_LAS bf16x8*)(lds + PG8_SB(b, h) + boff + n * 2048 + k * 1024); } while (0)
; #define PG8_MMA(ai, bj, At, Bt) do { __builtin_amdgcn_s_setprio(1); _Pragma("unroll") for (int m = 0; m < 4; ++m) _Pragma("unroll") for (int n = 0; n < 2; ++n) _Pragma("unroll") for (int k = 0; k < 2; ++k) \
;         acc[ai][bj][m][n] = __builtin_amdgcn_mfma_f32_16x16x32_bf16(Bt[n][k], At[m][k], acc[ai][bj][m][n], 0, 0, 0); __builtin_amdgcn_s_setprio(0); } while (0)
; #define PG8_WAIT_V(n) asm volatile("s_waitcnt vmcnt(" #n ")" ::: "memory")
; #define PG8_WAIT_L(n) asm volatile("s_waitcnt lgkmcnt(" #n ")" ::: "memory")
; #define PG8_BAR __builtin_amdgcn_s_barrier()
; #define PG8_SCHED __builtin_amdgcn_sched_barrier(0)
; template <class Epi, class Sched, bool ALIGN_EPI = false, bool SP2 = false>
; __device__ __forceinline__ void gemm_phase(PG8_LAS unsigned char* lds, const Gemm g, const Sched& S, const Epi& E) {
;     ...
;             PG8_LDB(B0, 1, 0); PG8_LDB(B1, 1, 1); PG8_SCHED; PG8_LDA(At, 1, 0); PG8_STAGE(PG8_SA(0, 1), a2 + hstepA, voffA);
;             PG8_WAIT_V(8); PG8_WAIT_L(0); PG8_BAR; PG8_MMA(0, 0, At, B0); PG8_MMA(0, 1, At, B1); PG8_BAR; PG8_SCHED;
	s_add_i32 s47, 0, 0x18000
	v_add_u32_e32 v0, s47, v161
	s_add_i32 s57, 0, 0x1c000
	ds_read_b128 v[90:93], v0
	ds_read_b128 v[94:97], v0 offset:1024
	ds_read_b128 v[106:109], v0 offset:2048
	ds_read_b128 v[110:113], v0 offset:3072
	v_add_u32_e32 v0, s57, v161
	ds_read_b128 v[164:167], v0
	ds_read_b128 v[168:171], v0 offset:1024
	ds_read_b128 v[172:175], v0 offset:2048
	ds_read_b128 v[176:179], v0 offset:3072
	s_add_u32 s38, s38, 0x40000
	s_addc_u32 s39, s39, 0
	s_mov_b32 m0, s88
	v_lshl_add_u64 v[198:199], s[38:39], 0, v[146:147]
	ds_read_b128 v[180:183], v163 offset:32768
	ds_read_b128 v[184:187], v163 offset:33792
	ds_read_b128 v[188:191], v163 offset:34816
	ds_read_b128 v[208:211], v163 offset:35840
	ds_read_b128 v[212:215], v163 offset:36864
	ds_read_b128 v[216:219], v163 offset:37888
	ds_read_b128 v[234:237], v163 offset:38912
	ds_read_b128 v[238:241], v163 offset:39936
	global_load_lds_dwordx4 v[198:199], off
	v_lshl_add_u64 v[198:199], s[38:39], 0, v[150:151]
	s_mov_b32 m0, s89
	s_nop 0
	global_load_lds_dwordx4 v[198:199], off
	s_waitcnt vmcnt(8)
	s_waitcnt lgkmcnt(0)
	s_barrier
	s_setprio 1
	s_waitcnt lgkmcnt(0)
	v_mfma_f32_16x16x32_bf16 v[142:145], v[90:93], v[180:183], v[142:145]
	v_mfma_f32_16x16x32_bf16 v[138:141], v[106:109], v[180:183], v[138:141]
	v_mfma_f32_16x16x32_bf16 v[126:129], v[90:93], v[188:191], v[126:129]
	v_mfma_f32_16x16x32_bf16 v[122:125], v[106:109], v[188:191], v[122:125]
	v_mfma_f32_16x16x32_bf16 v[102:105], v[90:93], v[212:215], v[102:105]
	v_mfma_f32_16x16x32_bf16 v[98:101], v[106:109], v[212:215], v[98:101]
	v_mfma_f32_16x16x32_bf16 v[78:81], v[90:93], v[234:237], v[78:81]
	v_mfma_f32_16x16x32_bf16 v[74:77], v[106:109], v[234:237], v[74:77]
	v_mfma_f32_16x16x32_bf16 v[142:145], v[94:97], v[184:187], v[142:145]
	v_mfma_f32_16x16x32_bf16 v[138:141], v[110:113], v[184:187], v[138:141]
	v_mfma_f32_16x16x32_bf16 v[126:129], v[94:97], v[208:211], v[126:129]
	v_mfma_f32_16x16x32_bf16 v[122:125], v[110:113], v[208:211], v[122:125]
	v_mfma_f32_16x16x32_bf16 v[102:105], v[94:97], v[216:219], v[102:105]
	v_mfma_f32_16x16x32_bf16 v[98:101], v[110:113], v[216:219], v[98:101]
	v_mfma_f32_16x16x32_bf16 v[78:81], v[94:97], v[238:241], v[78:81]
	v_mfma_f32_16x16x32_bf16 v[74:77], v[110:113], v[238:241], v[74:77]
	s_setprio 0
	s_setprio 1
	v_mfma_f32_16x16x32_bf16 v[134:137], v[164:167], v[180:183], v[134:137]
	v_mfma_f32_16x16x32_bf16 v[130:133], v[172:175], v[180:183], v[130:133]
	v_mfma_f32_16x16x32_bf16 v[118:121], v[164:167], v[188:191], v[118:121]
	v_mfma_f32_16x16x32_bf16 v[114:117], v[172:175], v[188:191], v[114:117]
	v_mfma_f32_16x16x32_bf16 v[86:89], v[164:167], v[212:215], v[86:89]
	v_mfma_f32_16x16x32_bf16 v[82:85], v[172:175], v[212:215], v[82:85]
	v_mfma_f32_16x16x32_bf16 v[70:73], v[164:167], v[234:237], v[70:73]
	v_mfma_f32_16x16x32_bf16 v[66:69], v[172:175], v[234:237], v[66:69]
	v_mfma_f32_16x16x32_bf16 v[134:137], v[168:171], v[184:187], v[134:137]
	v_mfma_f32_16x16x32_bf16 v[130:133], v[176:179], v[184:187], v[130:133]
	v_mfma_f32_16x16x32_bf16 v[118:121], v[168:171], v[208:211], v[118:121]
	v_mfma_f32_16x16x32_bf16 v[114:117], v[176:179], v[208:211], v[114:117]
	v_mfma_f32_16x16x32_bf16 v[86:89], v[168:171], v[216:219], v[86:89]
	v_mfma_f32_16x16x32_bf16 v[82:85], v[176:179], v[216:219], v[82:85]
	v_mfma_f32_16x16x32_bf16 v[70:73], v[168:171], v[238:241], v[70:73]
	v_mfma_f32_16x16x32_bf16 v[66:69], v[176:179], v[238:241], v[66:69]
	s_setprio 0
	s_barrier
; #define PG8_STAGE(bufoff, gbase, voff) do { _Pragma("unroll") for (int _i = 0; _i < 2; ++_i) \
;         __builtin_amdgcn_global_load_lds((const unsigned*)((const char*)(gbase) + (voff)[_i]), (PG8_LAS unsigned*)(lds + (bufoff) + ldsw + _i * 8192), 16, 0, 0); } while (0)
; #define PG8_LDA(dst, b, h) do { _Pragma("unroll") for (int m = 0; m < 4; ++m) _Pragma("unroll") for (int k = 0; k < 2; ++k) dst[m][k] = *(const PG8_LAS bf16x8*)(lds + PG8_SA(b, h) + aoff + m * 2048 + k * 1024); } while (0)
; #define PG8_MMA(ai, bj, At, Bt) do { __builtin_amdgcn_s_setprio(1); _Pragma("unroll") for (int m = 0; m < 4; ++m) _Pragma("unroll") for (int n = 0; n < 2; ++n) _Pragma("unroll") for (int k = 0; k < 2; ++k) \
;         acc[ai][bj][m][n] = __builtin_amdgcn_mfma_f32_16x16x32_bf16(Bt[n][k], At[m][k], acc[ai][bj][m][n], 0, 0, 0); __builtin_amdgcn_s_setprio(0); } while (0)
; #define PG8_WAIT_V(n) asm volatile("s_waitcnt vmcnt(" #n ")" ::: "memory")
; #define PG8_WAIT_L(n) asm volatile("s_waitcnt lgkmcnt(" #n ")" ::: "memory")
; #define PG8_BAR __builtin_amdgcn_s_barrier()
; #define PG8_SCHED __builtin_amdgcn_sched_barrier(0)
; template <class Epi, class Sched, bool ALIGN_EPI = false, bool SP2 = false>
; __device__ __forceinline__ void gemm_phase(PG8_LAS unsigned char* lds, const Gemm g, const Sched& S, const Epi& E) {
;     ...
;         for (int t = 0; t < nt; t += 2) {
;     ...
;             PG8_LDA(At, 1, 1); PG8_STAGE(PG8_SB(1, 0), b3, voffB); PG8_STAGE(PG8_SB(1, 1), b3 + hstepB, voffB); PG8_STAGE(PG8_SA(1, 0), a3, voffA);
;             PG8_WAIT_V(8); PG8_WAIT_L(0); PG8_BAR; PG8_MMA(1, 0, At, B0); PG8_MMA(1, 1, At, B1); PG8_BAR; PG8_SCHED;
	s_add_i32 s38, s47, s73
	v_lshl_add_u64 v[158:159], v[158:159], 0, s[22:23]
	s_mov_b32 m0, s38
	ds_read_b128 v[180:183], v163 offset:49152
	ds_read_b128 v[184:187], v163 offset:50176
	ds_read_b128 v[188:191], v163 offset:51200
	ds_read_b128 v[208:211], v163 offset:52224
	ds_read_b128 v[212:215], v163 offset:53248
	ds_read_b128 v[216:219], v163 offset:54272
	ds_read_b128 v[234:237], v163 offset:55296
	ds_read_b128 v[238:241], v163 offset:56320
	global_load_lds_dwordx4 v[158:159], off
	s_add_i32 m0, s38, 0x2000
	s_add_u32 s34, s34, 0x40080
	v_lshl_add_u64 v[158:159], v[192:193], 0, s[22:23]
	s_addc_u32 s35, s35, 0
	s_add_i32 s38, s57, s73
	global_load_lds_dwordx4 v[158:159], off
	v_lshl_add_u64 v[158:159], s[34:35], 0, v[148:149]
	s_mov_b32 m0, s38
	s_nop 0
	global_load_lds_dwordx4 v[158:159], off
	v_lshl_add_u64 v[158:159], s[34:35], 0, v[152:153]
	s_add_i32 m0, s38, 0x2000
	s_nop 0
	global_load_lds_dwordx4 v[158:159], off
	v_lshl_add_u64 v[158:159], v[194:195], 0, s[22:23]
	s_mov_b32 m0, s51
	s_nop 0
	global_load_lds_dwordx4 v[158:159], off
	v_lshl_add_u64 v[158:159], v[196:197], 0, s[22:23]
	s_mov_b32 m0, s94
	s_nop 0
	global_load_lds_dwordx4 v[158:159], off
	s_waitcnt vmcnt(8)
	s_waitcnt lgkmcnt(0)
	s_barrier
	s_setprio 1
	s_waitcnt lgkmcnt(0)
	v_mfma_f32_16x16x32_bf16 v[62:65], v[90:93], v[180:183], v[62:65]
	v_mfma_f32_16x16x32_bf16 v[58:61], v[106:109], v[180:183], v[58:61]
	v_mfma_f32_16x16x32_bf16 v[46:49], v[90:93], v[188:191], v[46:49]
	v_mfma_f32_16x16x32_bf16 v[42:45], v[106:109], v[188:191], v[42:45]
	v_mfma_f32_16x16x32_bf16 v[30:33], v[90:93], v[212:215], v[30:33]
	v_mfma_f32_16x16x32_bf16 v[26:29], v[106:109], v[212:215], v[26:29]
	v_mfma_f32_16x16x32_bf16 v[14:17], v[90:93], v[234:237], v[14:17]
	v_mfma_f32_16x16x32_bf16 v[10:13], v[106:109], v[234:237], v[10:13]
	v_mfma_f32_16x16x32_bf16 v[62:65], v[94:97], v[184:187], v[62:65]
	v_mfma_f32_16x16x32_bf16 v[58:61], v[110:113], v[184:187], v[58:61]
	v_mfma_f32_16x16x32_bf16 v[46:49], v[94:97], v[208:211], v[46:49]
	v_mfma_f32_16x16x32_bf16 v[42:45], v[110:113], v[208:211], v[42:45]
	v_mfma_f32_16x16x32_bf16 v[30:33], v[94:97], v[216:219], v[30:33]
	v_mfma_f32_16x16x32_bf16 v[26:29], v[110:113], v[216:219], v[26:29]
	v_mfma_f32_16x16x32_bf16 v[14:17], v[94:97], v[238:241], v[14:17]
	v_mfma_f32_16x16x32_bf16 v[10:13], v[110:113], v[238:241], v[10:13]
	s_setprio 0
	s_setprio 1
	v_mfma_f32_16x16x32_bf16 v[54:57], v[164:167], v[180:183], v[54:57]
	v_mfma_f32_16x16x32_bf16 v[50:53], v[172:175], v[180:183], v[50:53]
	v_mfma_f32_16x16x32_bf16 v[38:41], v[164:167], v[188:191], v[38:41]
	v_mfma_f32_16x16x32_bf16 v[34:37], v[172:175], v[188:191], v[34:37]
	v_mfma_f32_16x16x32_bf16 v[22:25], v[164:167], v[212:215], v[22:25]
	v_mfma_f32_16x16x32_bf16 v[18:21], v[172:175], v[212:215], v[18:21]
	v_mfma_f32_16x16x32_bf16 v[6:9], v[164:167], v[234:237], v[6:9]
	v_mfma_f32_16x16x32_bf16 v[2:5], v[172:175], v[234:237], v[2:5]
	v_mfma_f32_16x16x32_bf16 v[54:57], v[168:171], v[184:187], v[54:57]
	v_mfma_f32_16x16x32_bf16 v[50:53], v[176:179], v[184:187], v[50:53]
	v_mfma_f32_16x16x32_bf16 v[38:41], v[168:171], v[208:211], v[38:41]
	v_mfma_f32_16x16x32_bf16 v[34:37], v[176:179], v[208:211], v[34:37]
	v_mfma_f32_16x16x32_bf16 v[22:25], v[168:171], v[216:219], v[22:25]
	v_mfma_f32_16x16x32_bf16 v[18:21], v[176:179], v[216:219], v[18:21]
	v_mfma_f32_16x16x32_bf16 v[6:9], v[168:171], v[238:241], v[6:9]
	v_mfma_f32_16x16x32_bf16 v[2:5], v[176:179], v[238:241], v[2:5]
	s_setprio 0
	s_barrier
	s_add_i32 s45, s45, 2
	s_add_u32 s43, s43, 0x100
	s_addc_u32 s44, s44, 0
	s_add_u32 s6, s6, 0x100
	s_addc_u32 s7, s7, 0
	s_cmp_gt_u32 s45, 13
